# K-loops: rotating fragment-register read prefetch (6/8/4 quads at peerq/x1/mixed) with loads and LDS writes in MFMA gaps, auto-derived lgkmcnt waits
# speedup vs baseline: 1.0254x; 1.0019x over previous
; DI void gemm_ldg(const bf16_t* ga, const bf16_t* gb, int lda, int ldb, int koff, u32x4 (&ra)[4], u32x4 (&rb)[4]) {
; #pragma unroll
;   for (int i = 0; i < 4; ++i) {
;     ra[i] = *(const u32x4*)(ga + (size_t)(32 * i) * lda + koff);
;     rb[i] = *(const u32x4*)(gb + (size_t)(32 * i) * ldb + koff);
;   }
; }
; DI void gemm_sts(bf16_t* dA, bf16_t* dB, int r0, int c0, const u32x4 (&ra)[4], const u32x4 (&rb)[4]) {
; #pragma unroll
;   for (int i = 0; i < 4; ++i) {
;     *(u32x4*)(dA + (r0 + 32 * i) * LDT + c0 * 8) = ra[i];
;     *(u32x4*)(dB + (r0 + 32 * i) * LDT + c0 * 8) = rb[i];
;   }
; }
; DI void gemm_mma(const bf16_t* a_, const bf16_t* b_, f32x16 (&acc)[2][2]) {
;   __builtin_amdgcn_s_setprio(1);
; #pragma unroll
;   for (int kk = 0; kk < 4; ++kk) {
;     bf16x8 a0 = *(const bf16x8*)(a_ + kk * 16);
;     bf16x8 a1 = *(const bf16x8*)(a_ + 32 * LDT + kk * 16);
;     bf16x8 b0 = *(const bf16x8*)(b_ + kk * 16);
;     bf16x8 b1 = *(const bf16x8*)(b_ + 32 * LDT + kk * 16);
;     acc[0][0] = MFMA(a0, b0, acc[0][0]);
;     acc[0][1] = MFMA(a0, b1, acc[0][1]);
;     acc[1][0] = MFMA(a1, b0, acc[1][0]);
;     acc[1][1] = MFMA(a1, b1, acc[1][1]);
;   }
;   __builtin_amdgcn_s_setprio(0);
; }
; DI void gemm_tile(const bf16_t* __restrict__ A, int lda, const bf16_t* __restrict__ B, int ldb, int K,
;                   f32x16 (&acc)[2][2], char* smem) {
;   const int tid = threadIdx.x, lane = tid & 63, w = tid >> 6, wm = w >> 1, wn = w & 1;
;   bf16_t* sA = (bf16_t*)smem;
;   bf16_t* sB = sA + 2 * 128 * LDT;
;   const int r0 = tid >> 3, c0 = tid & 7;
;   const bf16_t* ga = A + (size_t)r0 * lda + c0 * 8;
;   const bf16_t* gb = B + (size_t)r0 * ldb + c0 * 8;
;   const int aoff = (wm * 64 + (lane & 31)) * LDT + (lane >> 5) * 8;
;   const int boff = (wn * 64 + (lane & 31)) * LDT + (lane >> 5) * 8;
;   u32x4 ra0[4], rb0[4], ra1[4], rb1[4];
;   gemm_ldg(ga, gb, lda, ldb, 0, ra0, rb0);
;   gemm_ldg(ga, gb, lda, ldb, 64, ra1, rb1);
;   __syncthreads();
;   gemm_sts(sA, sB, r0, c0, ra0, rb0);
;   __syncthreads();
;   const int nk = K >> 6;
; #pragma unroll 1
;   for (int kt = 0; kt < nk; kt += 2) {
;     if (kt + 2 < nk) gemm_ldg(ga, gb, lda, ldb, (kt + 2) * 64, ra0, rb0);
;     gemm_mma(sA + aoff, sB + boff, acc);
;     gemm_sts(sA + 128 * LDT, sB + 128 * LDT, r0, c0, ra1, rb1);
;     __syncthreads();
;     if (kt + 3 < nk) gemm_ldg(ga, gb, lda, ldb, (kt + 3) * 64, ra1, rb1);
.Lgf2_top:
	s_add_i32 s44, s44, 2
	s_cmp_lt_u32 s44, 14
	s_cselect_b64 s[42:43], -1, 0
	s_cmp_gt_u32 s44, 13
	s_cselect_b64 s[40:41], -1, 0
	s_and_b64 vcc, exec, s[40:41]
	v_lshl_add_u64 v[222:223], s[34:35], 0, v[160:161]
	v_lshl_add_u64 v[220:221], v[218:219], 0, v[158:159]
	ds_read_b128 v[240:243], v231
	ds_read_b128 v[244:247], v232 offset:36864
	ds_read_b128 v[248:251], v232 offset:41472
	ds_read_b128 v[252:255], v231 offset:4608
	s_setprio 1
	s_waitcnt lgkmcnt(2)
	v_mfma_f32_32x32x16_bf16 v[50:65], v[240:243], v[244:247], v[50:65]
	v_add_co_u32_e32 v66, vcc, 0x5300000, v222
	s_nop 1
	v_addc_co_u32_e32 v67, vcc, 0, v223, vcc
	v_add_co_u32_e32 v70, vcc, 0x680000, v220
	global_load_dwordx4 v[66:69], v[66:67], off offset:256
	s_waitcnt lgkmcnt(1)
	v_mfma_f32_32x32x16_bf16 v[34:49], v[240:243], v[248:251], v[34:49]
	ds_read_b128 v[240:243], v231 offset:32
	s_nop 0
	v_addc_co_u32_e32 v71, vcc, 0, v221, vcc
	v_add_co_u32_e32 v74, vcc, 0x5310000, v222
	global_load_dwordx4 v[70:73], v[70:71], off offset:256
	s_waitcnt lgkmcnt(1)
	v_mfma_f32_32x32x16_bf16 v[18:33], v[252:255], v[244:247], v[18:33]
	ds_read_b128 v[244:247], v232 offset:36896
	s_nop 0
	v_addc_co_u32_e32 v75, vcc, 0, v223, vcc
	v_add_co_u32_e32 v82, vcc, 0x690000, v220
	global_load_dwordx4 v[74:77], v[74:75], off offset:256
	s_waitcnt lgkmcnt(2)
	v_mfma_f32_32x32x16_bf16 v[2:17], v[252:255], v[248:251], v[2:17]
	ds_read_b128 v[248:251], v232 offset:41504
	ds_read_b128 v[252:255], v231 offset:4640
	s_nop 0
	v_addc_co_u32_e32 v83, vcc, 0, v221, vcc
	v_add_co_u32_e32 v86, vcc, 0x5320000, v222
	global_load_dwordx4 v[82:85], v[82:83], off offset:256
	s_waitcnt lgkmcnt(2)
	v_mfma_f32_32x32x16_bf16 v[50:65], v[240:243], v[244:247], v[50:65]
	s_nop 0
	v_addc_co_u32_e32 v87, vcc, 0, v223, vcc
	v_add_co_u32_e32 v94, vcc, 0x6a0000, v220
	global_load_dwordx4 v[86:89], v[86:87], off offset:256
	s_waitcnt lgkmcnt(1)
	v_mfma_f32_32x32x16_bf16 v[34:49], v[240:243], v[248:251], v[34:49]
	ds_read_b128 v[240:243], v231 offset:64
	s_nop 0
	v_addc_co_u32_e32 v95, vcc, 0, v221, vcc
	v_add_co_u32_e32 v102, vcc, 0x5330000, v222
	global_load_dwordx4 v[94:97], v[94:95], off offset:256
	s_waitcnt lgkmcnt(1)
	v_mfma_f32_32x32x16_bf16 v[18:33], v[252:255], v[244:247], v[18:33]
	ds_read_b128 v[244:247], v232 offset:36928
	s_nop 0
	v_addc_co_u32_e32 v103, vcc, 0, v223, vcc
	v_add_co_u32_e32 v110, vcc, s64, v220
	global_load_dwordx4 v[102:105], v[102:103], off offset:256
	s_waitcnt lgkmcnt(2)
	v_mfma_f32_32x32x16_bf16 v[2:17], v[252:255], v[248:251], v[2:17]
	ds_read_b128 v[248:251], v232 offset:41536
	ds_read_b128 v[252:255], v231 offset:4672
	s_nop 0
	v_addc_co_u32_e32 v111, vcc, 0, v221, vcc
	global_load_dwordx4 v[110:113], v[110:111], off offset:256
	s_waitcnt lgkmcnt(2)
	v_mfma_f32_32x32x16_bf16 v[50:65], v[240:243], v[244:247], v[50:65]
	s_waitcnt vmcnt(8)
	ds_write_b128 v230, v[78:81] offset:18432
	s_waitcnt lgkmcnt(2)
	v_mfma_f32_32x32x16_bf16 v[34:49], v[240:243], v[248:251], v[34:49]
	ds_read_b128 v[240:243], v231 offset:96
	ds_write_b128 v230, v[114:117] offset:55296
	s_waitcnt lgkmcnt(3)
	v_mfma_f32_32x32x16_bf16 v[18:33], v[252:255], v[244:247], v[18:33]
	ds_read_b128 v[244:247], v232 offset:36960
	ds_write_b128 v230, v[90:93] offset:23040
	s_waitcnt lgkmcnt(5)
	v_mfma_f32_32x32x16_bf16 v[2:17], v[252:255], v[248:251], v[2:17]
	ds_read_b128 v[248:251], v232 offset:41568
	ds_read_b128 v[252:255], v231 offset:4704
	ds_write_b128 v230, v[118:121] offset:59904
	s_waitcnt lgkmcnt(4)
	v_mfma_f32_32x32x16_bf16 v[50:65], v[240:243], v[244:247], v[50:65]
	ds_write_b128 v230, v[98:101] offset:27648
	s_waitcnt lgkmcnt(3)
	v_mfma_f32_32x32x16_bf16 v[34:49], v[240:243], v[248:251], v[34:49]
	ds_write_b128 v230, v[122:125] offset:64512
	s_waitcnt lgkmcnt(3)
	v_mfma_f32_32x32x16_bf16 v[18:33], v[252:255], v[244:247], v[18:33]
	ds_write_b128 v230, v[106:109] offset:32256
	s_waitcnt lgkmcnt(4)
	v_mfma_f32_32x32x16_bf16 v[2:17], v[252:255], v[248:251], v[2:17]
	ds_write_b128 v233, v[126:129] offset:13824
	s_setprio 0
	s_waitcnt lgkmcnt(0)
	s_barrier
; DI void gemm_ldg(const bf16_t* ga, const bf16_t* gb, int lda, int ldb, int koff, u32x4 (&ra)[4], u32x4 (&rb)[4]) {
; #pragma unroll
;   for (int i = 0; i < 4; ++i) {
;     ra[i] = *(const u32x4*)(ga + (size_t)(32 * i) * lda + koff);
;     rb[i] = *(const u32x4*)(gb + (size_t)(32 * i) * ldb + koff);
;   }
; }
; DI void gemm_sts(bf16_t* dA, bf16_t* dB, int r0, int c0, const u32x4 (&ra)[4], const u32x4 (&rb)[4]) {
; #pragma unroll
;   for (int i = 0; i < 4; ++i) {
;     *(u32x4*)(dA + (r0 + 32 * i) * LDT + c0 * 8) = ra[i];
;     *(u32x4*)(dB + (r0 + 32 * i) * LDT + c0 * 8) = rb[i];
;   }
; }
; DI void gemm_mma(const bf16_t* a_, const bf16_t* b_, f32x16 (&acc)[2][2]) {
;   __builtin_amdgcn_s_setprio(1);
; #pragma unroll
;   for (int kk = 0; kk < 4; ++kk) {
;     bf16x8 a0 = *(const bf16x8*)(a_ + kk * 16);
;     bf16x8 a1 = *(const bf16x8*)(a_ + 32 * LDT + kk * 16);
;     bf16x8 b0 = *(const bf16x8*)(b_ + kk * 16);
;     bf16x8 b1 = *(const bf16x8*)(b_ + 32 * LDT + kk * 16);
;     acc[0][0] = MFMA(a0, b0, acc[0][0]);
;     acc[0][1] = MFMA(a0, b1, acc[0][1]);
;     acc[1][0] = MFMA(a1, b0, acc[1][0]);
;     acc[1][1] = MFMA(a1, b1, acc[1][1]);
;   }
;   __builtin_amdgcn_s_setprio(0);
; }
; DI void gemm_tile(const bf16_t* __restrict__ A, int lda, const bf16_t* __restrict__ B, int ldb, int K,
;                   f32x16 (&acc)[2][2], char* smem) {
;   const int tid = threadIdx.x, lane = tid & 63, w = tid >> 6, wm = w >> 1, wn = w & 1;
;   bf16_t* sA = (bf16_t*)smem;
;   bf16_t* sB = sA + 2 * 128 * LDT;
;   const int r0 = tid >> 3, c0 = tid & 7;
;   const bf16_t* ga = A + (size_t)r0 * lda + c0 * 8;
;   const bf16_t* gb = B + (size_t)r0 * ldb + c0 * 8;
;   const int aoff = (wm * 64 + (lane & 31)) * LDT + (lane >> 5) * 8;
;   const int boff = (wn * 64 + (lane & 31)) * LDT + (lane >> 5) * 8;
;   u32x4 ra0[4], rb0[4], ra1[4], rb1[4];
;   gemm_ldg(ga, gb, lda, ldb, 0, ra0, rb0);
;   gemm_ldg(ga, gb, lda, ldb, 64, ra1, rb1);
;   __syncthreads();
;   gemm_sts(sA, sB, r0, c0, ra0, rb0);
;   __syncthreads();
;   const int nk = K >> 6;
; #pragma unroll 1
;   for (int kt = 0; kt < nk; kt += 2) {
;     if (kt + 2 < nk) gemm_ldg(ga, gb, lda, ldb, (kt + 2) * 64, ra0, rb0);
;     gemm_mma(sA + aoff, sB + boff, acc);
;     gemm_sts(sA + 128 * LDT, sB + 128 * LDT, r0, c0, ra1, rb1);
;     __syncthreads();
;     if (kt + 3 < nk) gemm_ldg(ga, gb, lda, ldb, (kt + 3) * 64, ra1, rb1);
	ds_read_b128 v[240:243], v231 offset:18432
	ds_read_b128 v[244:247], v232 offset:55296
	ds_read_b128 v[248:251], v232 offset:59904
	ds_read_b128 v[252:255], v231 offset:23040
	s_setprio 1
	s_waitcnt lgkmcnt(2)
	v_mfma_f32_32x32x16_bf16 v[50:65], v[240:243], v[244:247], v[50:65]
	v_add_co_u32_e32 v78, vcc, 0x5300000, v222
	s_nop 1
	v_addc_co_u32_e32 v79, vcc, 0, v223, vcc
	v_add_co_u32_e32 v90, vcc, 0x680000, v220
	global_load_dwordx4 v[78:81], v[78:79], off offset:384
	s_waitcnt lgkmcnt(1)
	v_mfma_f32_32x32x16_bf16 v[34:49], v[240:243], v[248:251], v[34:49]
	ds_read_b128 v[240:243], v231 offset:18464
	s_nop 0
	v_addc_co_u32_e32 v91, vcc, 0, v221, vcc
	global_load_dwordx4 v[114:117], v[90:91], off offset:384
	s_waitcnt lgkmcnt(1)
	v_mfma_f32_32x32x16_bf16 v[18:33], v[252:255], v[244:247], v[18:33]
	ds_read_b128 v[244:247], v232 offset:55328
	v_add_co_u32_e32 v90, vcc, 0x5310000, v222
	s_nop 1
	v_addc_co_u32_e32 v91, vcc, 0, v223, vcc
	v_add_co_u32_e32 v98, vcc, 0x690000, v220
	global_load_dwordx4 v[90:93], v[90:91], off offset:384
	s_waitcnt lgkmcnt(2)
	v_mfma_f32_32x32x16_bf16 v[2:17], v[252:255], v[248:251], v[2:17]
	ds_read_b128 v[248:251], v232 offset:59936
	ds_read_b128 v[252:255], v231 offset:23072
	s_nop 0
	v_addc_co_u32_e32 v99, vcc, 0, v221, vcc
	global_load_dwordx4 v[118:121], v[98:99], off offset:384
	s_waitcnt lgkmcnt(2)
	v_mfma_f32_32x32x16_bf16 v[50:65], v[240:243], v[244:247], v[50:65]
	v_add_co_u32_e32 v98, vcc, 0x5320000, v222
	s_nop 1
	v_addc_co_u32_e32 v99, vcc, 0, v223, vcc
	v_add_co_u32_e32 v106, vcc, 0x6a0000, v220
	global_load_dwordx4 v[98:101], v[98:99], off offset:384
	s_waitcnt lgkmcnt(1)
	v_mfma_f32_32x32x16_bf16 v[34:49], v[240:243], v[248:251], v[34:49]
	ds_read_b128 v[240:243], v231 offset:18496
	s_nop 0
	v_addc_co_u32_e32 v107, vcc, 0, v221, vcc
	global_load_dwordx4 v[122:125], v[106:107], off offset:384
	s_waitcnt lgkmcnt(1)
	v_mfma_f32_32x32x16_bf16 v[18:33], v[252:255], v[244:247], v[18:33]
	ds_read_b128 v[244:247], v232 offset:55360
	v_add_co_u32_e32 v106, vcc, 0x5330000, v222
	s_nop 1
	v_addc_co_u32_e32 v107, vcc, 0, v223, vcc
	v_add_co_u32_e32 v126, vcc, 0x6b0000, v220
	global_load_dwordx4 v[106:109], v[106:107], off offset:384
	s_waitcnt lgkmcnt(2)
	v_mfma_f32_32x32x16_bf16 v[2:17], v[252:255], v[248:251], v[2:17]
	ds_read_b128 v[248:251], v232 offset:59968
	ds_read_b128 v[252:255], v231 offset:23104
	s_nop 0
	v_addc_co_u32_e32 v127, vcc, 0, v221, vcc
	global_load_dwordx4 v[126:129], v[126:127], off offset:384
	s_waitcnt lgkmcnt(2)
	v_mfma_f32_32x32x16_bf16 v[50:65], v[240:243], v[244:247], v[50:65]
	s_waitcnt vmcnt(8)
	ds_write_b128 v230, v[66:69]
	s_waitcnt lgkmcnt(2)
	v_mfma_f32_32x32x16_bf16 v[34:49], v[240:243], v[248:251], v[34:49]
	ds_read_b128 v[240:243], v231 offset:18528
	ds_write_b128 v230, v[70:73] offset:36864
	s_waitcnt lgkmcnt(3)
	v_mfma_f32_32x32x16_bf16 v[18:33], v[252:255], v[244:247], v[18:33]
	ds_read_b128 v[244:247], v232 offset:55392
	ds_write_b128 v230, v[74:77] offset:4608
	s_waitcnt lgkmcnt(5)
	v_mfma_f32_32x32x16_bf16 v[2:17], v[252:255], v[248:251], v[2:17]
	ds_read_b128 v[248:251], v232 offset:60000
	ds_read_b128 v[252:255], v231 offset:23136
	ds_write_b128 v230, v[82:85] offset:41472
	s_waitcnt lgkmcnt(4)
	v_mfma_f32_32x32x16_bf16 v[50:65], v[240:243], v[244:247], v[50:65]
	ds_write_b128 v230, v[86:89] offset:9216
	s_waitcnt lgkmcnt(3)
	v_mfma_f32_32x32x16_bf16 v[34:49], v[240:243], v[248:251], v[34:49]
	ds_write_b128 v230, v[94:97] offset:46080
	s_waitcnt lgkmcnt(3)
	v_mfma_f32_32x32x16_bf16 v[18:33], v[252:255], v[244:247], v[18:33]
	ds_write_b128 v230, v[102:105] offset:13824
	s_waitcnt lgkmcnt(4)
	v_mfma_f32_32x32x16_bf16 v[2:17], v[252:255], v[248:251], v[2:17]
	ds_write_b128 v230, v[110:113] offset:50688
	s_setprio 0
	s_add_u32 s34, s34, 0x100
	s_addc_u32 s35, s35, 0
	s_andn2_b64 vcc, exec, s[40:41]
	v_lshl_add_u64 v[218:219], v[218:219], 0, s[24:25]
	s_waitcnt lgkmcnt(0)
	s_barrier
	s_cmp_lt_u32 s44, 12
	s_cbranch_scc1 .Lgf2_top
	s_branch .LBB0_288

; DI void gemm_ldg(const bf16_t* ga, const bf16_t* gb, int lda, int ldb, int koff, u32x4 (&ra)[4], u32x4 (&rb)[4]) {
; #pragma unroll
;   for (int i = 0; i < 4; ++i) {
;     ra[i] = *(const u32x4*)(ga + (size_t)(32 * i) * lda + koff);
;     rb[i] = *(const u32x4*)(gb + (size_t)(32 * i) * ldb + koff);
;   }
; }
; DI void gemm_sts(bf16_t* dA, bf16_t* dB, int r0, int c0, const u32x4 (&ra)[4], const u32x4 (&rb)[4]) {
; #pragma unroll
;   for (int i = 0; i < 4; ++i) {
;     *(u32x4*)(dA + (r0 + 32 * i) * LDT + c0 * 8) = ra[i];
;     *(u32x4*)(dB + (r0 + 32 * i) * LDT + c0 * 8) = rb[i];
;   }
; }
; DI void gemm_mma(const bf16_t* a_, const bf16_t* b_, f32x16 (&acc)[2][2]) {
;   __builtin_amdgcn_s_setprio(1);
; #pragma unroll
;   for (int kk = 0; kk < 4; ++kk) {
;     bf16x8 a0 = *(const bf16x8*)(a_ + kk * 16);
;     bf16x8 a1 = *(const bf16x8*)(a_ + 32 * LDT + kk * 16);
;     bf16x8 b0 = *(const bf16x8*)(b_ + kk * 16);
;     bf16x8 b1 = *(const bf16x8*)(b_ + 32 * LDT + kk * 16);
;     acc[0][0] = MFMA(a0, b0, acc[0][0]);
;     acc[0][1] = MFMA(a0, b1, acc[0][1]);
;     acc[1][0] = MFMA(a1, b0, acc[1][0]);
;     acc[1][1] = MFMA(a1, b1, acc[1][1]);
;   }
;   __builtin_amdgcn_s_setprio(0);
; }
; DI void gemm_tile(const bf16_t* __restrict__ A, int lda, const bf16_t* __restrict__ B, int ldb, int K,
;                   f32x16 (&acc)[2][2], char* smem) {
;   const int tid = threadIdx.x, lane = tid & 63, w = tid >> 6, wm = w >> 1, wn = w & 1;
;   bf16_t* sA = (bf16_t*)smem;
;   bf16_t* sB = sA + 2 * 128 * LDT;
;   const int r0 = tid >> 3, c0 = tid & 7;
;   const bf16_t* ga = A + (size_t)r0 * lda + c0 * 8;
;   const bf16_t* gb = B + (size_t)r0 * ldb + c0 * 8;
;   const int aoff = (wm * 64 + (lane & 31)) * LDT + (lane >> 5) * 8;
;   const int boff = (wn * 64 + (lane & 31)) * LDT + (lane >> 5) * 8;
;   u32x4 ra0[4], rb0[4], ra1[4], rb1[4];
;   gemm_ldg(ga, gb, lda, ldb, 0, ra0, rb0);
;   gemm_ldg(ga, gb, lda, ldb, 64, ra1, rb1);
;   __syncthreads();
;   gemm_sts(sA, sB, r0, c0, ra0, rb0);
;   __syncthreads();
;   const int nk = K >> 6;
; #pragma unroll 1
;   for (int kt = 0; kt < nk; kt += 2) {
;     if (kt + 2 < nk) gemm_ldg(ga, gb, lda, ldb, (kt + 2) * 64, ra0, rb0);
;     gemm_mma(sA + aoff, sB + boff, acc);
;     gemm_sts(sA + 128 * LDT, sB + 128 * LDT, r0, c0, ra1, rb1);
;     __syncthreads();
;     if (kt + 3 < nk) gemm_ldg(ga, gb, lda, ldb, (kt + 3) * 64, ra1, rb1);
.Lgf3_top:
	s_add_i32 s10, s10, 2
	s_cmp_lt_u32 s10, 14
	s_cselect_b64 s[20:21], -1, 0
	s_cmp_gt_u32 s10, 13
	s_cselect_b64 s[18:19], -1, 0
	s_and_b64 vcc, exec, s[18:19]
	v_lshl_add_u64 v[152:153], v[148:149], 0, v[144:145]
	v_lshl_add_u64 v[150:151], v[146:147], 0, v[144:145]
	ds_read_b128 v[208:211], v155
	ds_read_b128 v[212:215], v156 offset:36864
	ds_read_b128 v[216:219], v156 offset:41472
	ds_read_b128 v[220:223], v155 offset:4608
	ds_read_b128 v[232:235], v155 offset:32
	ds_read_b128 v[236:239], v156 offset:36896
	ds_read_b128 v[240:243], v156 offset:41504
	ds_read_b128 v[244:247], v155 offset:4640
	s_setprio 1
	s_waitcnt lgkmcnt(6)
	v_mfma_f32_32x32x16_bf16 v[50:65], v[208:211], v[212:215], v[50:65]
	v_add_co_u32_e32 v66, vcc, 0x15300000, v152
	s_nop 1
	v_addc_co_u32_e32 v67, vcc, 0, v153, vcc
	v_add_co_u32_e32 v70, vcc, 0xc00000, v150
	global_load_dwordx4 v[66:69], v[66:67], off offset:256
	s_waitcnt lgkmcnt(5)
	v_mfma_f32_32x32x16_bf16 v[34:49], v[208:211], v[216:219], v[34:49]
	ds_read_b128 v[208:211], v155 offset:64
	s_nop 0
	v_addc_co_u32_e32 v71, vcc, 0, v151, vcc
	v_add_co_u32_e32 v74, vcc, 0x15310000, v152
	global_load_dwordx4 v[70:73], v[70:71], off offset:256
	s_waitcnt lgkmcnt(5)
	v_mfma_f32_32x32x16_bf16 v[18:33], v[220:223], v[212:215], v[18:33]
	ds_read_b128 v[212:215], v156 offset:36928
	s_nop 0
	v_addc_co_u32_e32 v75, vcc, 0, v153, vcc
	v_add_co_u32_e32 v82, vcc, 0xc10000, v150
	global_load_dwordx4 v[74:77], v[74:75], off offset:256
	s_waitcnt lgkmcnt(6)
	v_mfma_f32_32x32x16_bf16 v[2:17], v[220:223], v[216:219], v[2:17]
	ds_read_b128 v[216:219], v156 offset:41536
	ds_read_b128 v[220:223], v155 offset:4672
	s_nop 0
	v_addc_co_u32_e32 v83, vcc, 0, v151, vcc
	v_add_co_u32_e32 v90, vcc, 0x15320000, v152
	global_load_dwordx4 v[82:85], v[82:83], off offset:256
	s_waitcnt lgkmcnt(6)
	v_mfma_f32_32x32x16_bf16 v[50:65], v[232:235], v[236:239], v[50:65]
	s_nop 0
	v_addc_co_u32_e32 v91, vcc, 0, v153, vcc
	v_add_co_u32_e32 v98, vcc, 0xc20000, v150
	global_load_dwordx4 v[90:93], v[90:91], off offset:256
	s_waitcnt lgkmcnt(5)
	v_mfma_f32_32x32x16_bf16 v[34:49], v[232:235], v[240:243], v[34:49]
	ds_read_b128 v[232:235], v155 offset:96
	s_nop 0
	v_addc_co_u32_e32 v99, vcc, 0, v151, vcc
	v_add_co_u32_e32 v110, vcc, 0x15330000, v152
	global_load_dwordx4 v[98:101], v[98:99], off offset:256
	s_waitcnt lgkmcnt(5)
	v_mfma_f32_32x32x16_bf16 v[18:33], v[244:247], v[236:239], v[18:33]
	ds_read_b128 v[236:239], v156 offset:36960
	s_nop 0
	v_addc_co_u32_e32 v111, vcc, 0, v153, vcc
	v_add_co_u32_e32 v126, vcc, s28, v150
	global_load_dwordx4 v[110:113], v[110:111], off offset:256
	s_waitcnt lgkmcnt(6)
	v_mfma_f32_32x32x16_bf16 v[2:17], v[244:247], v[240:243], v[2:17]
	ds_read_b128 v[240:243], v156 offset:41568
	ds_read_b128 v[244:247], v155 offset:4704
	s_nop 0
	v_addc_co_u32_e32 v127, vcc, 0, v151, vcc
	global_load_dwordx4 v[126:129], v[126:127], off offset:256
	s_waitcnt lgkmcnt(6)
	v_mfma_f32_32x32x16_bf16 v[50:65], v[208:211], v[212:215], v[50:65]
	s_waitcnt vmcnt(8)
	ds_write_b128 v154, v[78:81] offset:18432
	s_waitcnt lgkmcnt(6)
	v_mfma_f32_32x32x16_bf16 v[34:49], v[208:211], v[216:219], v[34:49]
	ds_write_b128 v154, v[86:89] offset:55296
	s_waitcnt lgkmcnt(6)
	v_mfma_f32_32x32x16_bf16 v[18:33], v[220:223], v[212:215], v[18:33]
	ds_write_b128 v154, v[94:97] offset:23040
	s_waitcnt lgkmcnt(7)
	v_mfma_f32_32x32x16_bf16 v[2:17], v[220:223], v[216:219], v[2:17]
	ds_write_b128 v154, v[102:105] offset:59904
	s_waitcnt lgkmcnt(6)
	v_mfma_f32_32x32x16_bf16 v[50:65], v[232:235], v[236:239], v[50:65]
	ds_write_b128 v154, v[106:109] offset:27648
	s_waitcnt lgkmcnt(6)
	v_mfma_f32_32x32x16_bf16 v[34:49], v[232:235], v[240:243], v[34:49]
	ds_write_b128 v154, v[118:121] offset:64512
	s_waitcnt lgkmcnt(6)
	v_mfma_f32_32x32x16_bf16 v[18:33], v[244:247], v[236:239], v[18:33]
	ds_write_b128 v154, v[114:117] offset:32256
	s_waitcnt lgkmcnt(7)
	v_mfma_f32_32x32x16_bf16 v[2:17], v[244:247], v[240:243], v[2:17]
	ds_write_b128 v157, v[122:125] offset:13824
	s_setprio 0
	s_waitcnt lgkmcnt(0)
	s_barrier
; DI void gemm_ldg(const bf16_t* ga, const bf16_t* gb, int lda, int ldb, int koff, u32x4 (&ra)[4], u32x4 (&rb)[4]) {
; #pragma unroll
;   for (int i = 0; i < 4; ++i) {
;     ra[i] = *(const u32x4*)(ga + (size_t)(32 * i) * lda + koff);
;     rb[i] = *(const u32x4*)(gb + (size_t)(32 * i) * ldb + koff);
;   }
; }
; DI void gemm_sts(bf16_t* dA, bf16_t* dB, int r0, int c0, const u32x4 (&ra)[4], const u32x4 (&rb)[4]) {
; #pragma unroll
;   for (int i = 0; i < 4; ++i) {
;     *(u32x4*)(dA + (r0 + 32 * i) * LDT + c0 * 8) = ra[i];
;     *(u32x4*)(dB + (r0 + 32 * i) * LDT + c0 * 8) = rb[i];
;   }
; }
; DI void gemm_mma(const bf16_t* a_, const bf16_t* b_, f32x16 (&acc)[2][2]) {
;   __builtin_amdgcn_s_setprio(1);
; #pragma unroll
;   for (int kk = 0; kk < 4; ++kk) {
;     bf16x8 a0 = *(const bf16x8*)(a_ + kk * 16);
;     bf16x8 a1 = *(const bf16x8*)(a_ + 32 * LDT + kk * 16);
;     bf16x8 b0 = *(const bf16x8*)(b_ + kk * 16);
;     bf16x8 b1 = *(const bf16x8*)(b_ + 32 * LDT + kk * 16);
;     acc[0][0] = MFMA(a0, b0, acc[0][0]);
;     acc[0][1] = MFMA(a0, b1, acc[0][1]);
;     acc[1][0] = MFMA(a1, b0, acc[1][0]);
;     acc[1][1] = MFMA(a1, b1, acc[1][1]);
;   }
;   __builtin_amdgcn_s_setprio(0);
; }
; DI void gemm_tile(const bf16_t* __restrict__ A, int lda, const bf16_t* __restrict__ B, int ldb, int K,
;                   f32x16 (&acc)[2][2], char* smem) {
;   const int tid = threadIdx.x, lane = tid & 63, w = tid >> 6, wm = w >> 1, wn = w & 1;
;   bf16_t* sA = (bf16_t*)smem;
;   bf16_t* sB = sA + 2 * 128 * LDT;
;   const int r0 = tid >> 3, c0 = tid & 7;
;   const bf16_t* ga = A + (size_t)r0 * lda + c0 * 8;
;   const bf16_t* gb = B + (size_t)r0 * ldb + c0 * 8;
;   const int aoff = (wm * 64 + (lane & 31)) * LDT + (lane >> 5) * 8;
;   const int boff = (wn * 64 + (lane & 31)) * LDT + (lane >> 5) * 8;
;   u32x4 ra0[4], rb0[4], ra1[4], rb1[4];
;   gemm_ldg(ga, gb, lda, ldb, 0, ra0, rb0);
;   gemm_ldg(ga, gb, lda, ldb, 64, ra1, rb1);
;   __syncthreads();
;   gemm_sts(sA, sB, r0, c0, ra0, rb0);
;   __syncthreads();
;   const int nk = K >> 6;
; #pragma unroll 1
;   for (int kt = 0; kt < nk; kt += 2) {
;     if (kt + 2 < nk) gemm_ldg(ga, gb, lda, ldb, (kt + 2) * 64, ra0, rb0);
;     gemm_mma(sA + aoff, sB + boff, acc);
;     gemm_sts(sA + 128 * LDT, sB + 128 * LDT, r0, c0, ra1, rb1);
;     __syncthreads();
;     if (kt + 3 < nk) gemm_ldg(ga, gb, lda, ldb, (kt + 3) * 64, ra1, rb1);
	ds_read_b128 v[208:211], v155 offset:18432
	ds_read_b128 v[212:215], v156 offset:55296
	ds_read_b128 v[216:219], v156 offset:59904
	ds_read_b128 v[220:223], v155 offset:23040
	ds_read_b128 v[232:235], v155 offset:18464
	ds_read_b128 v[236:239], v156 offset:55328
	ds_read_b128 v[240:243], v156 offset:59936
	ds_read_b128 v[244:247], v155 offset:23072
	s_setprio 1
	s_waitcnt lgkmcnt(6)
	v_mfma_f32_32x32x16_bf16 v[50:65], v[208:211], v[212:215], v[50:65]
	v_add_co_u32_e32 v78, vcc, 0x15300000, v152
	s_nop 1
	v_addc_co_u32_e32 v79, vcc, 0, v153, vcc
	v_add_co_u32_e32 v86, vcc, 0xc00000, v150
	global_load_dwordx4 v[78:81], v[78:79], off offset:384
	s_waitcnt lgkmcnt(5)
	v_mfma_f32_32x32x16_bf16 v[34:49], v[208:211], v[216:219], v[34:49]
	ds_read_b128 v[208:211], v155 offset:18496
	s_nop 0
	v_addc_co_u32_e32 v87, vcc, 0, v151, vcc
	v_add_co_u32_e32 v94, vcc, 0x15310000, v152
	global_load_dwordx4 v[86:89], v[86:87], off offset:384
	s_waitcnt lgkmcnt(5)
	v_mfma_f32_32x32x16_bf16 v[18:33], v[220:223], v[212:215], v[18:33]
	ds_read_b128 v[212:215], v156 offset:55360
	s_nop 0
	v_addc_co_u32_e32 v95, vcc, 0, v153, vcc
	v_add_co_u32_e32 v102, vcc, 0xc10000, v150
	global_load_dwordx4 v[94:97], v[94:95], off offset:384
	s_waitcnt lgkmcnt(6)
	v_mfma_f32_32x32x16_bf16 v[2:17], v[220:223], v[216:219], v[2:17]
	ds_read_b128 v[216:219], v156 offset:59968
	ds_read_b128 v[220:223], v155 offset:23104
	s_nop 0
	v_addc_co_u32_e32 v103, vcc, 0, v151, vcc
	v_add_co_u32_e32 v106, vcc, 0x15320000, v152
	global_load_dwordx4 v[102:105], v[102:103], off offset:384
	s_waitcnt lgkmcnt(6)
	v_mfma_f32_32x32x16_bf16 v[50:65], v[232:235], v[236:239], v[50:65]
	s_nop 0
	v_addc_co_u32_e32 v107, vcc, 0, v153, vcc
	v_add_co_u32_e32 v114, vcc, 0xc20000, v150
	global_load_dwordx4 v[106:109], v[106:107], off offset:384
	s_waitcnt lgkmcnt(5)
	v_mfma_f32_32x32x16_bf16 v[34:49], v[232:235], v[240:243], v[34:49]
	ds_read_b128 v[232:235], v155 offset:18528
	s_nop 0
	v_addc_co_u32_e32 v115, vcc, 0, v151, vcc
	global_load_dwordx4 v[118:121], v[114:115], off offset:384
	s_waitcnt lgkmcnt(5)
	v_mfma_f32_32x32x16_bf16 v[18:33], v[244:247], v[236:239], v[18:33]
	ds_read_b128 v[236:239], v156 offset:55392
	v_add_co_u32_e32 v114, vcc, 0x15330000, v152
	s_nop 1
	v_addc_co_u32_e32 v115, vcc, 0, v153, vcc
	v_add_co_u32_e32 v122, vcc, 0xc30000, v150
	global_load_dwordx4 v[114:117], v[114:115], off offset:384
	s_waitcnt lgkmcnt(6)
	v_mfma_f32_32x32x16_bf16 v[2:17], v[244:247], v[240:243], v[2:17]
	ds_read_b128 v[240:243], v156 offset:60000
	ds_read_b128 v[244:247], v155 offset:23136
	s_nop 0
	v_addc_co_u32_e32 v123, vcc, 0, v151, vcc
	global_load_dwordx4 v[122:125], v[122:123], off offset:384
	s_waitcnt lgkmcnt(6)
	v_mfma_f32_32x32x16_bf16 v[50:65], v[208:211], v[212:215], v[50:65]
	s_waitcnt vmcnt(8)
	ds_write_b128 v154, v[66:69]
	s_waitcnt lgkmcnt(6)
	v_mfma_f32_32x32x16_bf16 v[34:49], v[208:211], v[216:219], v[34:49]
	ds_write_b128 v154, v[70:73] offset:36864
	s_waitcnt lgkmcnt(6)
	v_mfma_f32_32x32x16_bf16 v[18:33], v[220:223], v[212:215], v[18:33]
	ds_write_b128 v154, v[74:77] offset:4608
	s_waitcnt lgkmcnt(7)
	v_mfma_f32_32x32x16_bf16 v[2:17], v[220:223], v[216:219], v[2:17]
	ds_write_b128 v154, v[82:85] offset:41472
	s_waitcnt lgkmcnt(6)
	v_mfma_f32_32x32x16_bf16 v[50:65], v[232:235], v[236:239], v[50:65]
	ds_write_b128 v154, v[90:93] offset:9216
	s_waitcnt lgkmcnt(6)
	v_mfma_f32_32x32x16_bf16 v[34:49], v[232:235], v[240:243], v[34:49]
	ds_write_b128 v154, v[98:101] offset:46080
	s_waitcnt lgkmcnt(6)
	v_mfma_f32_32x32x16_bf16 v[18:33], v[244:247], v[236:239], v[18:33]
	ds_write_b128 v154, v[110:113] offset:13824
	s_waitcnt lgkmcnt(7)
	v_mfma_f32_32x32x16_bf16 v[2:17], v[244:247], v[240:243], v[2:17]
	ds_write_b128 v154, v[126:129] offset:50688
	s_setprio 0
	v_lshl_add_u64 v[146:147], v[146:147], 0, s[16:17]
	s_andn2_b64 vcc, exec, s[18:19]
	v_lshl_add_u64 v[148:149], v[148:149], 0, s[16:17]
	s_waitcnt lgkmcnt(0)
	s_barrier
	s_cmp_lt_u32 s10, 12
	s_cbranch_scc1 .Lgf3_top
	s_branch .LBB0_335

; DI void gemm_ldg(const bf16_t* ga, const bf16_t* gb, int lda, int ldb, int koff, u32x4 (&ra)[4], u32x4 (&rb)[4]) {
; #pragma unroll
;   for (int i = 0; i < 4; ++i) {
;     ra[i] = *(const u32x4*)(ga + (size_t)(32 * i) * lda + koff);
;     rb[i] = *(const u32x4*)(gb + (size_t)(32 * i) * ldb + koff);
;   }
; }
; DI void gemm_sts(bf16_t* dA, bf16_t* dB, int r0, int c0, const u32x4 (&ra)[4], const u32x4 (&rb)[4]) {
; #pragma unroll
;   for (int i = 0; i < 4; ++i) {
;     *(u32x4*)(dA + (r0 + 32 * i) * LDT + c0 * 8) = ra[i];
;     *(u32x4*)(dB + (r0 + 32 * i) * LDT + c0 * 8) = rb[i];
;   }
; }
; DI void gemm_mma(const bf16_t* a_, const bf16_t* b_, f32x16 (&acc)[2][2]) {
;   __builtin_amdgcn_s_setprio(1);
; #pragma unroll
;   for (int kk = 0; kk < 4; ++kk) {
;     bf16x8 a0 = *(const bf16x8*)(a_ + kk * 16);
;     bf16x8 a1 = *(const bf16x8*)(a_ + 32 * LDT + kk * 16);
;     bf16x8 b0 = *(const bf16x8*)(b_ + kk * 16);
;     bf16x8 b1 = *(const bf16x8*)(b_ + 32 * LDT + kk * 16);
;     acc[0][0] = MFMA(a0, b0, acc[0][0]);
;     acc[0][1] = MFMA(a0, b1, acc[0][1]);
;     acc[1][0] = MFMA(a1, b0, acc[1][0]);
;     acc[1][1] = MFMA(a1, b1, acc[1][1]);
;   }
;   __builtin_amdgcn_s_setprio(0);
; }
; DI void gemm_tile(const bf16_t* __restrict__ A, int lda, const bf16_t* __restrict__ B, int ldb, int K,
;                   f32x16 (&acc)[2][2], char* smem) {
;   const int tid = threadIdx.x, lane = tid & 63, w = tid >> 6, wm = w >> 1, wn = w & 1;
;   bf16_t* sA = (bf16_t*)smem;
;   bf16_t* sB = sA + 2 * 128 * LDT;
;   const int r0 = tid >> 3, c0 = tid & 7;
;   const bf16_t* ga = A + (size_t)r0 * lda + c0 * 8;
;   const bf16_t* gb = B + (size_t)r0 * ldb + c0 * 8;
;   const int aoff = (wm * 64 + (lane & 31)) * LDT + (lane >> 5) * 8;
;   const int boff = (wn * 64 + (lane & 31)) * LDT + (lane >> 5) * 8;
;   u32x4 ra0[4], rb0[4], ra1[4], rb1[4];
;   gemm_ldg(ga, gb, lda, ldb, 0, ra0, rb0);
;   gemm_ldg(ga, gb, lda, ldb, 64, ra1, rb1);
;   __syncthreads();
;   gemm_sts(sA, sB, r0, c0, ra0, rb0);
;   __syncthreads();
;   const int nk = K >> 6;
; #pragma unroll 1
;   for (int kt = 0; kt < nk; kt += 2) {
;     if (kt + 2 < nk) gemm_ldg(ga, gb, lda, ldb, (kt + 2) * 64, ra0, rb0);
;     gemm_mma(sA + aoff, sB + boff, acc);
;     gemm_sts(sA + 128 * LDT, sB + 128 * LDT, r0, c0, ra1, rb1);
;     __syncthreads();
;     if (kt + 3 < nk) gemm_ldg(ga, gb, lda, ldb, (kt + 3) * 64, ra1, rb1);
.Lgf4_top:
	s_add_i32 s99, s99, 2
	s_cmp_lt_u32 s99, 14
	s_cselect_b64 s[88:89], -1, 0
	s_cmp_gt_u32 s99, 13
	s_cselect_b64 s[86:87], -1, 0
	s_and_b64 vcc, exec, s[86:87]
	v_lshl_add_u64 v[194:195], v[190:191], 0, s[68:69]
	v_lshl_add_u64 v[192:193], v[190:191], 0, s[44:45]
	ds_read_b128 v[232:235], v203
	ds_read_b128 v[236:239], v204 offset:36864
	ds_read_b128 v[240:243], v204 offset:41472
	ds_read_b128 v[244:247], v203 offset:4608
	ds_read_b128 v[248:251], v203 offset:32
	ds_read_b128 v[252:255], v204 offset:36896
	s_setprio 1
	s_waitcnt lgkmcnt(4)
	v_mfma_f32_32x32x16_bf16 v[50:65], v[232:235], v[236:239], v[50:65]
	v_add_co_u32_e32 v66, vcc, 0x5300000, v194
	s_nop 1
	v_addc_co_u32_e32 v67, vcc, 0, v195, vcc
	v_add_co_u32_e32 v70, vcc, 0xe00000, v192
	s_nop 1
	v_addc_co_u32_e32 v71, vcc, 0, v193, vcc
	v_add_co_u32_e32 v78, vcc, 0x5310000, v194
	global_load_dwordx4 v[66:69], v[66:67], off offset:256
	s_waitcnt lgkmcnt(3)
	v_mfma_f32_32x32x16_bf16 v[34:49], v[232:235], v[240:243], v[34:49]
	ds_read_b128 v[232:235], v204 offset:41504
	s_nop 0
	global_load_dwordx4 v[70:73], v[70:71], off offset:256
	s_waitcnt lgkmcnt(3)
	v_mfma_f32_32x32x16_bf16 v[18:33], v[244:247], v[236:239], v[18:33]
	ds_read_b128 v[236:239], v203 offset:4640
	v_addc_co_u32_e32 v79, vcc, 0, v195, vcc
	v_add_co_u32_e32 v82, vcc, 0xe10000, v192
	s_nop 1
	v_addc_co_u32_e32 v83, vcc, 0, v193, vcc
	v_add_co_u32_e32 v90, vcc, 0x5320000, v194
	global_load_dwordx4 v[78:81], v[78:79], off offset:256
	s_waitcnt lgkmcnt(4)
	v_mfma_f32_32x32x16_bf16 v[2:17], v[244:247], v[240:243], v[2:17]
	ds_read_b128 v[240:243], v203 offset:64
	ds_read_b128 v[244:247], v204 offset:36928
	s_nop 0
	global_load_dwordx4 v[82:85], v[82:83], off offset:256
	s_waitcnt lgkmcnt(4)
	v_mfma_f32_32x32x16_bf16 v[50:65], v[248:251], v[252:255], v[50:65]
	v_addc_co_u32_e32 v91, vcc, 0, v195, vcc
	v_add_co_u32_e32 v94, vcc, 0xe20000, v192
	s_nop 1
	v_addc_co_u32_e32 v95, vcc, 0, v193, vcc
	v_add_co_u32_e32 v110, vcc, 0x5330000, v194
	global_load_dwordx4 v[90:93], v[90:91], off offset:256
	s_waitcnt lgkmcnt(3)
	v_mfma_f32_32x32x16_bf16 v[34:49], v[248:251], v[232:235], v[34:49]
	ds_read_b128 v[248:251], v204 offset:41536
	s_nop 0
	global_load_dwordx4 v[94:97], v[94:95], off offset:256
	s_waitcnt lgkmcnt(3)
	v_mfma_f32_32x32x16_bf16 v[18:33], v[236:239], v[252:255], v[18:33]
	ds_read_b128 v[252:255], v203 offset:4672
	v_addc_co_u32_e32 v111, vcc, 0, v195, vcc
	v_add_co_u32_e32 v118, vcc, s90, v192
	s_nop 1
	v_addc_co_u32_e32 v119, vcc, 0, v193, vcc
	global_load_dwordx4 v[110:113], v[110:111], off offset:256
	s_waitcnt lgkmcnt(4)
	v_mfma_f32_32x32x16_bf16 v[2:17], v[236:239], v[232:235], v[2:17]
	ds_read_b128 v[232:235], v203 offset:96
	ds_read_b128 v[236:239], v204 offset:36960
	s_nop 0
	global_load_dwordx4 v[118:121], v[118:119], off offset:256
	s_waitcnt lgkmcnt(4)
	v_mfma_f32_32x32x16_bf16 v[50:65], v[240:243], v[244:247], v[50:65]
	s_waitcnt vmcnt(8)
	ds_write_b128 v202, v[74:77] offset:18432
	s_waitcnt lgkmcnt(4)
	v_mfma_f32_32x32x16_bf16 v[34:49], v[240:243], v[248:251], v[34:49]
	ds_read_b128 v[240:243], v204 offset:41568
	ds_write_b128 v202, v[106:109] offset:55296
	s_waitcnt lgkmcnt(5)
	v_mfma_f32_32x32x16_bf16 v[18:33], v[252:255], v[244:247], v[18:33]
	ds_read_b128 v[244:247], v203 offset:4704
	ds_write_b128 v202, v[86:89] offset:23040
	s_waitcnt lgkmcnt(7)
	v_mfma_f32_32x32x16_bf16 v[2:17], v[252:255], v[248:251], v[2:17]
	ds_write_b128 v202, v[114:117] offset:59904
	s_waitcnt lgkmcnt(6)
	v_mfma_f32_32x32x16_bf16 v[50:65], v[232:235], v[236:239], v[50:65]
	ds_write_b128 v202, v[98:101] offset:27648
	s_waitcnt lgkmcnt(5)
	v_mfma_f32_32x32x16_bf16 v[34:49], v[232:235], v[240:243], v[34:49]
	ds_write_b128 v202, v[122:125] offset:64512
	s_waitcnt lgkmcnt(4)
	v_mfma_f32_32x32x16_bf16 v[18:33], v[244:247], v[236:239], v[18:33]
	ds_write_b128 v202, v[102:105] offset:32256
	s_waitcnt lgkmcnt(5)
	v_mfma_f32_32x32x16_bf16 v[2:17], v[244:247], v[240:243], v[2:17]
	ds_write_b128 v205, v[126:129] offset:13824
	s_setprio 0
	s_waitcnt lgkmcnt(0)
	s_barrier
; DI void gemm_ldg(const bf16_t* ga, const bf16_t* gb, int lda, int ldb, int koff, u32x4 (&ra)[4], u32x4 (&rb)[4]) {
; #pragma unroll
;   for (int i = 0; i < 4; ++i) {
;     ra[i] = *(const u32x4*)(ga + (size_t)(32 * i) * lda + koff);
;     rb[i] = *(const u32x4*)(gb + (size_t)(32 * i) * ldb + koff);
;   }
; }
; DI void gemm_sts(bf16_t* dA, bf16_t* dB, int r0, int c0, const u32x4 (&ra)[4], const u32x4 (&rb)[4]) {
; #pragma unroll
;   for (int i = 0; i < 4; ++i) {
;     *(u32x4*)(dA + (r0 + 32 * i) * LDT + c0 * 8) = ra[i];
;     *(u32x4*)(dB + (r0 + 32 * i) * LDT + c0 * 8) = rb[i];
;   }
; }
; DI void gemm_mma(const bf16_t* a_, const bf16_t* b_, f32x16 (&acc)[2][2]) {
;   __builtin_amdgcn_s_setprio(1);
; #pragma unroll
;   for (int kk = 0; kk < 4; ++kk) {
;     bf16x8 a0 = *(const bf16x8*)(a_ + kk * 16);
;     bf16x8 a1 = *(const bf16x8*)(a_ + 32 * LDT + kk * 16);
;     bf16x8 b0 = *(const bf16x8*)(b_ + kk * 16);
;     bf16x8 b1 = *(const bf16x8*)(b_ + 32 * LDT + kk * 16);
;     acc[0][0] = MFMA(a0, b0, acc[0][0]);
;     acc[0][1] = MFMA(a0, b1, acc[0][1]);
;     acc[1][0] = MFMA(a1, b0, acc[1][0]);
;     acc[1][1] = MFMA(a1, b1, acc[1][1]);
;   }
;   __builtin_amdgcn_s_setprio(0);
; }
; DI void gemm_tile(const bf16_t* __restrict__ A, int lda, const bf16_t* __restrict__ B, int ldb, int K,
;                   f32x16 (&acc)[2][2], char* smem) {
;   const int tid = threadIdx.x, lane = tid & 63, w = tid >> 6, wm = w >> 1, wn = w & 1;
;   bf16_t* sA = (bf16_t*)smem;
;   bf16_t* sB = sA + 2 * 128 * LDT;
;   const int r0 = tid >> 3, c0 = tid & 7;
;   const bf16_t* ga = A + (size_t)r0 * lda + c0 * 8;
;   const bf16_t* gb = B + (size_t)r0 * ldb + c0 * 8;
;   const int aoff = (wm * 64 + (lane & 31)) * LDT + (lane >> 5) * 8;
;   const int boff = (wn * 64 + (lane & 31)) * LDT + (lane >> 5) * 8;
;   u32x4 ra0[4], rb0[4], ra1[4], rb1[4];
;   gemm_ldg(ga, gb, lda, ldb, 0, ra0, rb0);
;   gemm_ldg(ga, gb, lda, ldb, 64, ra1, rb1);
;   __syncthreads();
;   gemm_sts(sA, sB, r0, c0, ra0, rb0);
;   __syncthreads();
;   const int nk = K >> 6;
; #pragma unroll 1
;   for (int kt = 0; kt < nk; kt += 2) {
;     if (kt + 2 < nk) gemm_ldg(ga, gb, lda, ldb, (kt + 2) * 64, ra0, rb0);
;     gemm_mma(sA + aoff, sB + boff, acc);
;     gemm_sts(sA + 128 * LDT, sB + 128 * LDT, r0, c0, ra1, rb1);
;     __syncthreads();
;     if (kt + 3 < nk) gemm_ldg(ga, gb, lda, ldb, (kt + 3) * 64, ra1, rb1);
	ds_read_b128 v[232:235], v203 offset:18432
	ds_read_b128 v[236:239], v204 offset:55296
	ds_read_b128 v[240:243], v204 offset:59904
	ds_read_b128 v[244:247], v203 offset:23040
	ds_read_b128 v[248:251], v203 offset:18464
	ds_read_b128 v[252:255], v204 offset:55328
	s_setprio 1
	s_waitcnt lgkmcnt(4)
	v_mfma_f32_32x32x16_bf16 v[50:65], v[232:235], v[236:239], v[50:65]
	v_add_co_u32_e32 v74, vcc, 0x5300000, v194
	s_nop 1
	v_addc_co_u32_e32 v75, vcc, 0, v195, vcc
	v_add_co_u32_e32 v86, vcc, 0xe00000, v192
	s_nop 1
	v_addc_co_u32_e32 v87, vcc, 0, v193, vcc
	global_load_dwordx4 v[74:77], v[74:75], off offset:384
	s_waitcnt lgkmcnt(3)
	v_mfma_f32_32x32x16_bf16 v[34:49], v[232:235], v[240:243], v[34:49]
	ds_read_b128 v[232:235], v204 offset:59936
	s_nop 0
	global_load_dwordx4 v[106:109], v[86:87], off offset:384
	s_waitcnt lgkmcnt(3)
	v_mfma_f32_32x32x16_bf16 v[18:33], v[244:247], v[236:239], v[18:33]
	ds_read_b128 v[236:239], v203 offset:23072
	v_add_co_u32_e32 v86, vcc, 0x5310000, v194
	s_nop 1
	v_addc_co_u32_e32 v87, vcc, 0, v195, vcc
	v_add_co_u32_e32 v98, vcc, 0xe10000, v192
	s_nop 1
	v_addc_co_u32_e32 v99, vcc, 0, v193, vcc
	global_load_dwordx4 v[86:89], v[86:87], off offset:384
	s_waitcnt lgkmcnt(4)
	v_mfma_f32_32x32x16_bf16 v[2:17], v[244:247], v[240:243], v[2:17]
	ds_read_b128 v[240:243], v203 offset:18496
	ds_read_b128 v[244:247], v204 offset:55360
	s_nop 0
	global_load_dwordx4 v[114:117], v[98:99], off offset:384
	s_waitcnt lgkmcnt(4)
	v_mfma_f32_32x32x16_bf16 v[50:65], v[248:251], v[252:255], v[50:65]
	v_add_co_u32_e32 v98, vcc, 0x5320000, v194
	s_nop 1
	v_addc_co_u32_e32 v99, vcc, 0, v195, vcc
	v_add_co_u32_e32 v102, vcc, 0xe20000, v192
	s_nop 1
	v_addc_co_u32_e32 v103, vcc, 0, v193, vcc
	global_load_dwordx4 v[98:101], v[98:99], off offset:384
	s_waitcnt lgkmcnt(3)
	v_mfma_f32_32x32x16_bf16 v[34:49], v[248:251], v[232:235], v[34:49]
	ds_read_b128 v[248:251], v204 offset:59968
	s_nop 0
	global_load_dwordx4 v[122:125], v[102:103], off offset:384
	s_waitcnt lgkmcnt(3)
	v_mfma_f32_32x32x16_bf16 v[18:33], v[236:239], v[252:255], v[18:33]
	ds_read_b128 v[252:255], v203 offset:23104
	v_add_co_u32_e32 v102, vcc, 0x5330000, v194
	s_nop 1
	v_addc_co_u32_e32 v103, vcc, 0, v195, vcc
	v_add_co_u32_e32 v126, vcc, 0xe30000, v192
	s_nop 1
	v_addc_co_u32_e32 v127, vcc, 0, v193, vcc
	global_load_dwordx4 v[102:105], v[102:103], off offset:384
	s_waitcnt lgkmcnt(4)
	v_mfma_f32_32x32x16_bf16 v[2:17], v[236:239], v[232:235], v[2:17]
	ds_read_b128 v[232:235], v203 offset:18528
	ds_read_b128 v[236:239], v204 offset:55392
	s_nop 0
	global_load_dwordx4 v[126:129], v[126:127], off offset:384
	s_waitcnt lgkmcnt(4)
	v_mfma_f32_32x32x16_bf16 v[50:65], v[240:243], v[244:247], v[50:65]
	s_waitcnt vmcnt(8)
	ds_write_b128 v202, v[66:69]
	s_waitcnt lgkmcnt(4)
	v_mfma_f32_32x32x16_bf16 v[34:49], v[240:243], v[248:251], v[34:49]
	ds_read_b128 v[240:243], v204 offset:60000
	ds_write_b128 v202, v[70:73] offset:36864
	s_waitcnt lgkmcnt(5)
	v_mfma_f32_32x32x16_bf16 v[18:33], v[252:255], v[244:247], v[18:33]
	ds_read_b128 v[244:247], v203 offset:23136
	ds_write_b128 v202, v[78:81] offset:4608
	s_waitcnt lgkmcnt(7)
	v_mfma_f32_32x32x16_bf16 v[2:17], v[252:255], v[248:251], v[2:17]
	ds_write_b128 v202, v[82:85] offset:41472
	s_waitcnt lgkmcnt(6)
	v_mfma_f32_32x32x16_bf16 v[50:65], v[232:235], v[236:239], v[50:65]
	ds_write_b128 v202, v[90:93] offset:9216
	s_waitcnt lgkmcnt(5)
	v_mfma_f32_32x32x16_bf16 v[34:49], v[232:235], v[240:243], v[34:49]
	ds_write_b128 v202, v[94:97] offset:46080
	s_waitcnt lgkmcnt(4)
	v_mfma_f32_32x32x16_bf16 v[18:33], v[244:247], v[236:239], v[18:33]
	ds_write_b128 v202, v[110:113] offset:13824
	s_waitcnt lgkmcnt(5)
	v_mfma_f32_32x32x16_bf16 v[2:17], v[244:247], v[240:243], v[2:17]
	ds_write_b128 v202, v[118:121] offset:50688
	s_setprio 0
	s_andn2_b64 vcc, exec, s[86:87]
	v_lshl_add_u64 v[190:191], v[190:191], 0, s[64:65]
	s_waitcnt lgkmcnt(0)
	s_barrier
	s_cmp_lt_u32 s99, 12
	s_cbranch_scc1 .Lgf4_top
	s_branch .LBB0_462
